# attention phase: one static s_setprio 1 for the upper wave half, per-cluster priority flips removed
# speedup vs baseline: 1.0085x; 1.0085x over previous
.LBB0_617:
	s_or_b64 exec, exec, s[2:3]
	v_readlane_b32 s0, v253, 61
	s_add_i32 s0, s0, s1
	s_cmpk_gt_i32 s0, 0x2fff
	s_waitcnt vmcnt(0) lgkmcnt(0)
	s_barrier
	s_cbranch_scc1 .LBB0_641
	v_ashrrev_i32_e32 v0, 4, v99
	v_lshlrev_b32_e32 v96, 3, v0
	v_lshlrev_b32_e32 v1, 4, v99
	v_lshlrev_b32_e32 v100, 2, v0
	v_bfe_u32 v0, v99, 2, 2
	s_mulk_i32 s1, 0x1200
	v_and_b32_e32 v104, 0x70, v1
	v_lshlrev_b32_e32 v1, 3, v99
	v_or_b32_e32 v0, v100, v0
	s_movk_i32 s2, 0x90
	s_add_i32 s1, s1, 0
	v_ashrrev_i32_e32 v103, 3, v99
	v_mul_lo_u32 v0, v0, s2
	v_and_b32_e32 v1, 24, v1
	v_and_b32_e32 v49, 15, v99
	v_add_u32_e32 v2, s1, v104
	v_add3_u32 v106, s1, v0, v1
	v_mul_lo_u32 v0, v103, s2
	v_lshlrev_b32_e32 v102, 4, v49
	v_ashrrev_i32_e32 v97, 31, v96
	v_and_b32_e32 v98, -16, v99
	v_subrev_u32_e32 v105, 64, v100
	v_add_u32_e32 v107, 0x900, v106
	v_ashrrev_i32_e32 v101, 31, v100
	v_add_u32_e32 v108, v2, v0
	s_bitcmp1_b32 s0, 2
	s_cbranch_scc0 .Lattprio_done
	s_setprio 1

.LBB0_619:
	v_add_f32_e32 v21, 0, v21
	v_add_f32_e32 v21, v22, v21
	v_add_f32_e32 v21, v23, v21
	v_add_f32_e32 v21, v24, v21
	v_add_f32_e32 v21, v25, v21
	v_add_f32_e32 v21, v26, v21
	v_add_f32_e32 v21, v27, v21
	v_add_f32_e32 v24, v28, v21
	v_fmac_f32_e32 v24, v112, v20
	ds_read_b64_tr_b16 v[114:115], v106 offset:16384
	ds_read_b64_tr_b16 v[116:117], v107 offset:16384
	ds_read_b64_tr_b16 v[118:119], v106 offset:16416
	ds_read_b64_tr_b16 v[120:121], v107 offset:16416
	ds_read_b64_tr_b16 v[122:123], v106 offset:16448
	ds_read_b64_tr_b16 v[124:125], v107 offset:16448
	ds_read_b64_tr_b16 v[126:127], v106 offset:16480
	ds_read_b64_tr_b16 v[128:129], v107 offset:16480
	s_waitcnt lgkmcnt(6)
	v_mfma_f32_16x16x32_bf16 v[8:11], v[114:117], v[16:19], v[8:11]
	s_waitcnt lgkmcnt(4)
	v_mfma_f32_16x16x32_bf16 v[4:7], v[118:121], v[16:19], v[4:7]
	s_waitcnt lgkmcnt(2)
	v_mfma_f32_16x16x32_bf16 v[0:3], v[122:125], v[16:19], v[0:3]
	s_waitcnt lgkmcnt(0)
	v_mfma_f32_16x16x32_bf16 v[12:15], v[126:129], v[16:19], v[12:15]
	v_and_b32_e32 v17, 64, v234
	v_xor_b32_e32 v16, 16, v234
	v_add_u32_e32 v17, 64, v17
	v_cmp_lt_i32_e32 vcc, v16, v17
	v_xor_b32_e32 v18, 32, v234
	s_add_i32 s0, s0, s82
	v_cndmask_b32_e32 v16, v234, v16, vcc
	v_lshlrev_b32_e32 v16, 2, v16
	ds_bpermute_b32 v16, v16, v24
	v_cmp_lt_i32_e32 vcc, v18, v17
	s_cmpk_gt_i32 s0, 0x2fff
	s_waitcnt lgkmcnt(0)
	v_add_f32_e32 v16, v24, v16
	v_cndmask_b32_e32 v17, v234, v18, vcc
	v_lshlrev_b32_e32 v17, 2, v17
	ds_bpermute_b32 v17, v17, v16
	s_waitcnt lgkmcnt(0)
	v_add_f32_e32 v16, v16, v17
	v_div_scale_f32 v17, s[6:7], v16, v16, 1.0
	v_rcp_f32_e32 v18, v17
	s_nop 0
	v_fma_f32 v19, -v17, v18, 1.0
	v_fmac_f32_e32 v18, v19, v18
	v_div_scale_f32 v19, vcc, 1.0, v16, 1.0
	v_mul_f32_e32 v20, v19, v18
	v_fma_f32 v21, -v17, v20, v19
	v_fmac_f32_e32 v20, v21, v18
	v_fma_f32 v17, -v17, v20, v19
	v_div_fmas_f32 v17, v17, v18, v20
	v_lshlrev_b64 v[18:19], 11, v[50:51]
	v_lshl_add_u64 v[18:19], s[24:25], 0, v[18:19]
	v_div_fixup_f32 v16, v17, v16, 1.0
	v_lshl_add_u64 v[18:19], s[2:3], 1, v[18:19]
	v_lshl_add_u64 v[18:19], v[100:101], 1, v[18:19]
	v_pk_mul_f32 v[8:9], v[8:9], v[16:17] op_sel_hi:[1,0]
	v_pk_mul_f32 v[4:5], v[4:5], v[16:17] op_sel_hi:[1,0]
	v_pk_mul_f32 v[2:3], v[2:3], v[16:17] op_sel_hi:[1,0]
	v_pk_mul_f32 v[0:1], v[0:1], v[16:17] op_sel_hi:[1,0]
	v_pk_mul_f32 v[10:11], v[10:11], v[16:17] op_sel_hi:[1,0]
	v_cvt_pk_bf16_f32 v8, v8, v9
	v_pk_mul_f32 v[6:7], v[6:7], v[16:17] op_sel_hi:[1,0]
	v_cvt_pk_bf16_f32 v9, v10, v11
	global_store_dwordx2 v[18:19], v[8:9], off
	v_cvt_pk_bf16_f32 v4, v4, v5
	v_cvt_pk_bf16_f32 v5, v6, v7
	global_store_dwordx2 v[18:19], v[4:5], off offset:32
	v_cvt_pk_bf16_f32 v0, v0, v1
	v_cvt_pk_bf16_f32 v1, v2, v3
	v_pk_mul_f32 v[2:3], v[12:13], v[16:17] op_sel_hi:[1,0]
	global_store_dwordx2 v[18:19], v[0:1], off offset:64
	v_pk_mul_f32 v[0:1], v[14:15], v[16:17] op_sel_hi:[1,0]
	v_cvt_pk_bf16_f32 v2, v2, v3
	s_nop 0
	v_cvt_pk_bf16_f32 v3, v0, v1
	global_store_dwordx2 v[18:19], v[2:3], off offset:96
	s_cbranch_scc1 .LBB0_641

.LBB0_629:
	s_lshl_b32 s20, -1, s13
	s_andn2_b32 s22, s10, s20
	s_lshr_b32 s20, s15, s13
	s_lshl_b32 s21, s21, 5
	s_add_i32 s20, s20, s21
	s_lshr_b32 s18, s14, s13
	s_sub_i32 s23, s20, 64
	v_add_u32_e32 v26, s23, v49
	s_add_i32 s18, s18, -1
	v_min_i32_e32 v24, s18, v26
	v_cmp_lt_i32_e32 vcc, -1, v26
	v_add_u32_e32 v56, s23, v103
	v_min_i32_e32 v44, s18, v56
	v_cndmask_b32_e32 v24, 0, v24, vcc
	v_lshlrev_b32_e32 v24, s13, v24
	v_add_u32_e32 v24, s22, v24
	v_mad_u64_u32 v[24:25], s[20:21], v24, s31, v[98:99]
	global_load_dwordx4 v[36:39], v24, s[6:7] offset:768
	global_load_dwordx4 v[40:43], v24, s[6:7] offset:832
	v_add_u32_e32 v24, 16, v26
	v_min_i32_e32 v25, s18, v24
	v_cmp_lt_i32_e32 vcc, -1, v24
	v_add_u32_e32 v45, 8, v56
	v_min_i32_e32 v45, s18, v45
	v_cndmask_b32_e32 v24, 0, v25, vcc
	v_cmp_lt_i32_e32 vcc, -1, v56
	v_add_u32_e32 v57, 16, v56
	v_min_i32_e32 v57, s18, v57
	v_cndmask_b32_e32 v44, 0, v44, vcc
	v_cmp_lt_i32_e32 vcc, -9, v56
	v_add_u32_e32 v58, 24, v56
	v_min_i32_e32 v58, s18, v58
	v_cndmask_b32_e32 v45, 0, v45, vcc
	v_cmp_lt_i32_e32 vcc, s55, v56
	v_lshlrev_b32_e32 v44, s13, v44
	v_lshlrev_b32_e32 v45, s13, v45
	v_cndmask_b32_e32 v57, 0, v57, vcc
	v_cmp_lt_i32_e32 vcc, s96, v56
	v_lshlrev_b32_e32 v57, s13, v57
	v_lshlrev_b32_e32 v24, s13, v24
	v_cndmask_b32_e32 v56, 0, v58, vcc
	v_lshlrev_b32_e32 v56, s13, v56
	v_add_u32_e32 v44, s22, v44
	v_add_u32_e32 v45, s22, v45
	v_add_u32_e32 v57, s22, v57
	v_add_u32_e32 v56, s22, v56
	v_add_u32_e32 v24, s22, v24
	v_mul_lo_u32 v44, v44, s31
	v_mul_lo_u32 v45, v45, s31
	v_mul_lo_u32 v57, v57, s31
	v_mul_lo_u32 v56, v56, s31
	v_mad_u64_u32 v[28:29], s[20:21], v24, s31, v[98:99]
	v_or_b32_e32 v44, v44, v104
	v_or_b32_e32 v52, v45, v104
	v_or_b32_e32 v57, v57, v104
	v_or_b32_e32 v60, v56, v104
	global_load_dwordx4 v[24:27], v28, s[6:7] offset:768
	s_nop 0
	global_load_dwordx4 v[28:31], v28, s[6:7] offset:832
	s_nop 0
	global_load_dwordx4 v[44:47], v44, s[6:7] offset:1536
	s_nop 0
	global_load_dwordx4 v[52:55], v52, s[6:7] offset:1536
	s_nop 0
	global_load_dwordx4 v[56:59], v57, s[6:7] offset:1536
	s_nop 0
	global_load_dwordx4 v[60:63], v60, s[6:7] offset:1536
	s_lshr_b32 s13, s15, s12
	v_lshrrev_b32_e32 v112, s12, v110
	s_lshl_b32 s18, s19, 5
	s_lshr_b32 s19, s14, s12
	s_lshr_b32 s12, s12, 1
	s_waitcnt vmcnt(11)
	ds_write_b128 v108, v[84:87] offset:16384
	s_waitcnt vmcnt(10)
	ds_write_b128 v108, v[80:83] offset:17536
	s_waitcnt vmcnt(9)
	ds_write_b128 v108, v[92:95] offset:18688
	s_waitcnt vmcnt(8)
	ds_write_b128 v108, v[88:91] offset:19840
	v_add_u32_e32 v80, s13, v105
	v_sub_u32_e32 v81, v80, v112
	s_mul_i32 s12, s12, 6
	v_add_u32_e32 v81, s18, v81
	s_add_i32 s12, s12, s1
	s_mulk_i32 s12, 0x210
	v_add_u32_e32 v83, 1, v81
	v_add_u32_e32 v85, 2, v81
	v_add_u32_e32 v87, 3, v81
	v_add_u32_e32 v89, 16, v81
	v_add_u32_e32 v91, 17, v81
	v_add_u32_e32 v93, 18, v81
	v_add_u32_e32 v95, 19, v81
	s_add_i32 s12, s12, 0
	v_med3_i32 v82, v81, s30, 64
	v_med3_i32 v84, v83, s30, 64
	v_med3_i32 v86, v85, s30, 64
	v_med3_i32 v88, v87, s30, 64
	v_med3_i32 v90, v89, s30, 64
	v_med3_i32 v92, v91, s30, 64
	v_med3_i32 v94, v93, s30, 64
	v_med3_i32 v113, v95, s30, 64
	v_lshl_add_u32 v82, v82, 2, s12
	v_lshl_add_u32 v84, v84, 2, s12
	v_lshl_add_u32 v86, v86, 2, s12
	v_lshl_add_u32 v88, v88, 2, s12
	v_lshl_add_u32 v90, v90, 2, s12
	v_lshl_add_u32 v92, v92, 2, s12
	v_lshl_add_u32 v94, v94, 2, s12
	v_lshl_add_u32 v113, v113, 2, s12
	ds_read_b32 v82, v82 offset:256
	ds_read_b32 v84, v84 offset:256
	ds_read_b32 v86, v86 offset:256
	ds_read_b32 v88, v88 offset:256
	ds_read_b32 v90, v90 offset:256
	ds_read_b32 v92, v92 offset:256
	ds_read_b32 v94, v94 offset:256
	ds_read_b32 v113, v113 offset:256
	s_waitcnt lgkmcnt(7)
	s_waitcnt lgkmcnt(6)
	s_waitcnt lgkmcnt(5)
	s_waitcnt lgkmcnt(4)
	s_waitcnt lgkmcnt(3)
	s_waitcnt lgkmcnt(2)
	s_waitcnt lgkmcnt(1)
	s_waitcnt lgkmcnt(0)
	v_mfma_f32_16x16x32_bf16 v[76:79], v[76:79], v[16:19], 0
	v_mfma_f32_16x16x32_bf16 v[72:75], v[72:75], v[20:23], v[76:79]
	s_nop 5
	v_add_u32_e32 v76, s18, v80
	v_add_u32_e32 v77, 64, v81
	v_cmp_gt_u32_e32 vcc, s97, v77
	v_cmp_gt_u32_e64 s[38:39], s19, v76
	v_fmac_f32_e32 v82, 0x3e000000, v72
	s_and_b64 vcc, vcc, s[38:39]
	v_add_u32_e32 v76, v83, v112
	v_add_u32_e32 v77, 0x41, v81
	v_cndmask_b32_e32 v72, v233, v82, vcc
	v_cmp_gt_u32_e32 vcc, s97, v77
	v_cmp_gt_u32_e64 s[38:39], s19, v76
	v_fmac_f32_e32 v84, 0x3e000000, v73
	s_and_b64 vcc, vcc, s[38:39]
	v_add_u32_e32 v76, v85, v112
	v_add_u32_e32 v77, 0x42, v81
	v_cndmask_b32_e32 v73, v233, v84, vcc
	v_cmp_gt_u32_e32 vcc, s97, v77
	v_cmp_gt_u32_e64 s[38:39], s19, v76
	v_fmac_f32_e32 v86, 0x3e000000, v74
	s_and_b64 vcc, vcc, s[38:39]
	v_add_u32_e32 v76, v87, v112
	v_add_u32_e32 v77, 0x43, v81
	v_cndmask_b32_e32 v74, v233, v86, vcc
	v_cmp_gt_u32_e32 vcc, s97, v77
	v_cmp_gt_u32_e64 s[38:39], s19, v76
	v_fmac_f32_e32 v88, 0x3e000000, v75
	s_and_b64 vcc, vcc, s[38:39]
	v_cndmask_b32_e32 v75, v233, v88, vcc
	v_mfma_f32_16x16x32_bf16 v[68:71], v[68:71], v[16:19], 0
	v_mfma_f32_16x16x32_bf16 v[64:67], v[64:67], v[20:23], v[68:71]
	s_nop 5
	v_add_u32_e32 v68, v89, v112
	v_add_u32_e32 v69, 0x50, v81
	v_cmp_gt_u32_e32 vcc, s97, v69
	v_cmp_gt_u32_e64 s[38:39], s19, v68
	v_fmac_f32_e32 v90, 0x3e000000, v64
	s_and_b64 vcc, vcc, s[38:39]
	v_add_u32_e32 v68, v91, v112
	v_add_u32_e32 v69, 0x51, v81
	v_cndmask_b32_e32 v64, v233, v90, vcc
	v_cmp_gt_u32_e32 vcc, s97, v69
	v_cmp_gt_u32_e64 s[38:39], s19, v68
	v_fmac_f32_e32 v92, 0x3e000000, v65
	s_and_b64 vcc, vcc, s[38:39]
	v_add_u32_e32 v68, v93, v112
	v_add_u32_e32 v69, 0x52, v81
	v_cndmask_b32_e32 v65, v233, v92, vcc
	v_cmp_gt_u32_e32 vcc, s97, v69
	v_cmp_gt_u32_e64 s[38:39], s19, v68
	v_fmac_f32_e32 v94, 0x3e000000, v66
	s_and_b64 vcc, vcc, s[38:39]
	v_add_u32_e32 v68, v95, v112
	v_add_u32_e32 v69, 0x53, v81
	v_cndmask_b32_e32 v66, v233, v94, vcc
	v_cmp_gt_u32_e32 vcc, s97, v69
	v_cmp_gt_u32_e64 s[38:39], s19, v68
	v_max_f32_e32 v68, v72, v73
	v_fmac_f32_e32 v113, 0x3e000000, v67
	s_and_b64 vcc, vcc, s[38:39]
	v_max3_f32 v68, v68, v74, v75
	v_cndmask_b32_e32 v67, v233, v113, vcc
	v_max3_f32 v68, v68, v64, v65
	v_max3_f32 v68, v68, v66, v67
	v_add_f32_e32 v69, 0x41000000, v109
	v_cmp_gt_f32_e32 vcc, v68, v69
	s_cmp_lg_u64 vcc, 0
	s_cselect_b64 s[12:13], -1, 0
	s_cbranch_vccz .LBB0_631
	v_and_b32_e32 v70, 64, v234
	v_xor_b32_e32 v69, 16, v234
	v_add_u32_e32 v70, 64, v70
	v_cmp_lt_i32_e32 vcc, v69, v70
	s_nop 1
	v_cndmask_b32_e32 v69, v234, v69, vcc
	v_lshlrev_b32_e32 v69, 2, v69
	ds_bpermute_b32 v69, v69, v68
	v_max_f32_e32 v68, v68, v68
	s_waitcnt lgkmcnt(0)
	v_max_f32_e32 v69, v69, v69
	v_max_f32_e32 v68, v68, v69
	v_xor_b32_e32 v69, 32, v234
	v_cmp_lt_i32_e32 vcc, v69, v70
	s_nop 1
	v_cndmask_b32_e32 v69, v234, v69, vcc
	v_lshlrev_b32_e32 v69, 2, v69
	ds_bpermute_b32 v69, v69, v68
	s_waitcnt lgkmcnt(0)
	v_max3_f32 v69, v109, v68, v69
	v_sub_f32_e32 v68, v109, v69
	v_mul_f32_e32 v68, 0x3fb8aa3b, v68
	v_exp_f32_e32 v68, v68
	v_mov_b32_e32 v109, v69
	s_branch .LBB0_632

.LBB0_634:
	v_add_f32_e32 v12, 0, v69
	v_add_f32_e32 v12, v70, v12
	v_add_f32_e32 v12, v71, v12
	v_add_f32_e32 v12, v72, v12
	v_add_f32_e32 v12, v73, v12
	v_add_f32_e32 v12, v74, v12
	v_add_f32_e32 v12, v75, v12
	v_add_f32_e32 v112, v76, v12
	ds_read_b64_tr_b16 v[114:115], v106 offset:16384
	ds_read_b64_tr_b16 v[116:117], v107 offset:16384
	ds_read_b64_tr_b16 v[118:119], v106 offset:16416
	ds_read_b64_tr_b16 v[120:121], v107 offset:16416
	ds_read_b64_tr_b16 v[122:123], v106 offset:16448
	ds_read_b64_tr_b16 v[124:125], v107 offset:16448
	ds_read_b64_tr_b16 v[126:127], v106 offset:16480
	ds_read_b64_tr_b16 v[128:129], v107 offset:16480
	v_fmac_f32_e32 v112, v111, v68
	s_waitcnt lgkmcnt(6)
	v_mfma_f32_16x16x32_bf16 v[8:11], v[114:117], v[64:67], v[8:11]
	s_waitcnt lgkmcnt(4)
	v_mfma_f32_16x16x32_bf16 v[4:7], v[118:121], v[64:67], v[4:7]
	s_waitcnt lgkmcnt(2)
	v_mfma_f32_16x16x32_bf16 v[0:3], v[122:125], v[64:67], v[0:3]
	s_waitcnt lgkmcnt(0)
	v_mfma_f32_16x16x32_bf16 v[12:15], v[126:129], v[64:67], v[32:35]
	s_add_i32 s16, s16, 1
	s_cmp_eq_u32 s16, 11
	s_cbranch_scc1 .LBB0_636
	s_waitcnt vmcnt(4)
	v_mov_b64_e32 v[66:67], v[30:31]
	v_mov_b64_e32 v[70:71], v[26:27]
	v_mov_b64_e32 v[74:75], v[42:43]
	v_mov_b64_e32 v[78:79], v[38:39]
	s_waitcnt vmcnt(0)
	v_mov_b64_e32 v[90:91], v[62:63]
	v_mov_b64_e32 v[94:95], v[58:59]
	v_mov_b64_e32 v[82:83], v[54:55]
	v_mov_b64_e32 v[86:87], v[46:47]
	v_mov_b64_e32 v[64:65], v[28:29]
	v_mov_b64_e32 v[68:69], v[24:25]
	v_mov_b64_e32 v[72:73], v[40:41]
	v_mov_b64_e32 v[76:77], v[36:37]
	v_mov_b64_e32 v[88:89], v[60:61]
	v_mov_b64_e32 v[92:93], v[56:57]
	v_mov_b64_e32 v[80:81], v[52:53]
	v_mov_b64_e32 v[84:85], v[44:45]
	v_mov_b32_e32 v111, v112
	s_mov_b32 s18, s17
	v_mov_b32_e32 v32, v12
	v_mov_b32_e32 v33, v13
	v_mov_b32_e32 v34, v14
	v_mov_b32_e32 v35, v15
	s_branch .LBB0_621
.LBB0_636:
	v_lshrrev_b32_e32 v32, 4, v110
	s_waitcnt vmcnt(3)
	ds_write_b128 v108, v[44:47] offset:16384
	s_waitcnt vmcnt(2)
	ds_write_b128 v108, v[52:55] offset:17536
	s_waitcnt vmcnt(1)
	ds_write_b128 v108, v[56:59] offset:18688
	s_waitcnt vmcnt(0)
	ds_write_b128 v108, v[60:63] offset:19840
	v_lshl_add_u32 v44, s11, 4, v105
	v_sub_u32_e32 v45, v44, v32
	s_movk_i32 s7, 0xff40
	v_med3_i32 v32, v45, s7, v235
	s_movk_i32 s7, 0xff3f
	v_med3_i32 v33, v45, s7, v236
	s_movk_i32 s7, 0xff3e
	v_med3_i32 v34, v45, s7, v237
	s_movk_i32 s7, 0xff3d
	v_med3_i32 v35, v45, s7, v238
	s_movk_i32 s7, 0xff30
	v_med3_i32 v46, v45, s7, v239
	s_movk_i32 s7, 0xff2f
	v_med3_i32 v47, v45, s7, v240
	s_movk_i32 s7, 0xff2e
	s_mulk_i32 s1, 0x210
	v_med3_i32 v52, v45, s7, v241
	s_movk_i32 s7, 0xff2d
	s_add_i32 s1, s1, 0
	v_med3_i32 v53, v45, s7, v242
	v_lshl_add_u32 v32, v32, 2, s1
	v_lshl_add_u32 v46, v46, 2, s1
	v_lshl_add_u32 v47, v47, 2, s1
	v_lshl_add_u32 v52, v52, 2, s1
	v_lshl_add_u32 v53, v53, 2, s1
	v_lshl_add_u32 v33, v33, 2, s1
	v_lshl_add_u32 v34, v34, 2, s1
	v_lshl_add_u32 v35, v35, 2, s1
	ds_read_b32 v54, v32 offset:7104
	ds_read_b32 v55, v33 offset:7108
	ds_read_b32 v56, v34 offset:7112
	ds_read_b32 v57, v35 offset:7116
	ds_read_b32 v46, v46 offset:7168
	ds_read_b32 v47, v47 offset:7172
	ds_read_b32 v52, v52 offset:7176
	ds_read_b32 v53, v53 offset:7180
	s_lshr_b32 s6, s14, 4
	s_waitcnt lgkmcnt(7)
	s_waitcnt lgkmcnt(6)
	s_waitcnt lgkmcnt(5)
	s_waitcnt lgkmcnt(4)
	s_waitcnt lgkmcnt(3)
	s_waitcnt lgkmcnt(2)
	s_waitcnt lgkmcnt(1)
	s_waitcnt lgkmcnt(0)
	v_mfma_f32_16x16x32_bf16 v[32:35], v[36:39], v[16:19], 0
	v_mfma_f32_16x16x32_bf16 v[32:35], v[40:43], v[20:23], v[32:35]
	v_add_u32_e32 v36, 0x80, v44
	v_add_u32_e32 v37, 0xc0, v45
	v_cmp_gt_u32_e32 vcc, s97, v37
	v_cmp_gt_u32_e64 s[38:39], s6, v36
	s_nop 2
	v_fmac_f32_e32 v54, 0x3e000000, v32
	s_and_b64 vcc, vcc, s[38:39]
	v_add_u32_e32 v36, 0x81, v44
	v_add_u32_e32 v37, 0xc1, v45
	v_cndmask_b32_e32 v32, v233, v54, vcc
	v_cmp_gt_u32_e32 vcc, s97, v37
	v_cmp_gt_u32_e64 s[38:39], s6, v36
	v_fmac_f32_e32 v55, 0x3e000000, v33
	s_and_b64 vcc, vcc, s[38:39]
	v_add_u32_e32 v36, 0x82, v44
	v_add_u32_e32 v37, 0xc2, v45
	v_cndmask_b32_e32 v33, v233, v55, vcc
	v_cmp_gt_u32_e32 vcc, s97, v37
	v_cmp_gt_u32_e64 s[38:39], s6, v36
	v_fmac_f32_e32 v56, 0x3e000000, v34
	s_and_b64 vcc, vcc, s[38:39]
	v_add_u32_e32 v36, 0x83, v44
	v_add_u32_e32 v37, 0xc3, v45
	v_cndmask_b32_e32 v34, v233, v56, vcc
	v_cmp_gt_u32_e32 vcc, s97, v37
	v_cmp_gt_u32_e64 s[38:39], s6, v36
	v_fmac_f32_e32 v57, 0x3e000000, v35
	s_and_b64 vcc, vcc, s[38:39]
	v_cndmask_b32_e32 v35, v233, v57, vcc
	v_mfma_f32_16x16x32_bf16 v[16:19], v[24:27], v[16:19], 0
	v_mfma_f32_16x16x32_bf16 v[16:19], v[28:31], v[20:23], v[16:19]
	v_add_u32_e32 v20, 0x90, v44
	v_add_u32_e32 v21, 0xd0, v45
	v_cmp_gt_u32_e32 vcc, s97, v21
	v_cmp_gt_u32_e64 s[38:39], s6, v20
	s_nop 2
	v_fmac_f32_e32 v46, 0x3e000000, v16
	s_and_b64 vcc, vcc, s[38:39]
	v_add_u32_e32 v20, 0x91, v44
	v_add_u32_e32 v21, 0xd1, v45
	v_cndmask_b32_e32 v16, v233, v46, vcc
	v_cmp_gt_u32_e32 vcc, s97, v21
	v_cmp_gt_u32_e64 s[38:39], s6, v20
	v_fmac_f32_e32 v47, 0x3e000000, v17
	s_and_b64 vcc, vcc, s[38:39]
	v_add_u32_e32 v20, 0x92, v44
	v_add_u32_e32 v21, 0xd2, v45
	v_cndmask_b32_e32 v17, v233, v47, vcc
	v_cmp_gt_u32_e32 vcc, s97, v21
	v_cmp_gt_u32_e64 s[38:39], s6, v20
	v_fmac_f32_e32 v52, 0x3e000000, v18
	s_and_b64 vcc, vcc, s[38:39]
	v_add_u32_e32 v20, 0x93, v44
	v_add_u32_e32 v21, 0xd3, v45
	v_cndmask_b32_e32 v18, v233, v52, vcc
	v_cmp_gt_u32_e32 vcc, s97, v21
	v_cmp_gt_u32_e64 s[38:39], s6, v20
	v_max_f32_e32 v20, v32, v33
	v_fmac_f32_e32 v53, 0x3e000000, v19
	s_and_b64 vcc, vcc, s[38:39]
	v_max3_f32 v20, v20, v34, v35
	v_cndmask_b32_e32 v19, v233, v53, vcc
	v_max3_f32 v20, v20, v16, v17
	v_max3_f32 v20, v20, v18, v19
	v_add_f32_e32 v21, 0x41000000, v109
	v_cmp_gt_f32_e32 vcc, v20, v21
	s_cmp_lg_u64 vcc, 0
	s_cselect_b64 s[6:7], -1, 0
	s_cbranch_vccz .LBB0_638
	v_and_b32_e32 v22, 64, v234
	v_xor_b32_e32 v21, 16, v234
	v_add_u32_e32 v22, 64, v22
	v_cmp_lt_i32_e32 vcc, v21, v22
	s_nop 1
	v_cndmask_b32_e32 v21, v234, v21, vcc
	v_lshlrev_b32_e32 v21, 2, v21
	ds_bpermute_b32 v21, v21, v20
	v_max_f32_e32 v20, v20, v20
	s_waitcnt lgkmcnt(0)
	v_max_f32_e32 v21, v21, v21
	v_max_f32_e32 v20, v20, v21
	v_xor_b32_e32 v21, 32, v234
	v_cmp_lt_i32_e32 vcc, v21, v22
	s_nop 1
	v_cndmask_b32_e32 v21, v234, v21, vcc
	v_lshlrev_b32_e32 v21, 2, v21
	ds_bpermute_b32 v21, v21, v20
	s_waitcnt lgkmcnt(0)
	v_max3_f32 v21, v109, v20, v21
	v_sub_f32_e32 v20, v109, v21
	v_mul_f32_e32 v20, 0x3fb8aa3b, v20
	v_exp_f32_e32 v20, v20
	v_mov_b32_e32 v109, v21
	s_branch .LBB0_639

.LBB0_641:
	s_setprio 0
	v_readlane_b32 s0, v251, 55
	s_nop 1
	v_add_u32_e32 v40, s0, v48
	s_mov_b32 s0, 0x100000
	v_cmp_gt_i32_e32 vcc, s0, v40
	s_and_saveexec_b64 s[2:3], vcc
	s_cbranch_execz .LBB0_652
	v_lshlrev_b32_e32 v41, 3, v40
	s_mov_b64 s[6:7], 0
	v_mov_b32_e32 v42, v40
	s_branch .LBB0_644
